# dense attention tile loop: workgroup barrier moved to mid-iteration, K fragments of the next tile read one tile ahead, four tiles staged ahead
# baseline (speedup 1.0000x reference)
.Lga_unit:
	v_and_b32_e32 v144, 63, v247
	s_and_b32 s80, s1, 15
	s_bfe_u32 s81, s1, 0x10004
	s_lshr_b32 s43, s1, 5
	s_lshl_b32 s0, s81, 7
	s_add_u32 s0, s0, 0x900
	s_add_u32 s6, s4, 0x9f00000
	s_addc_u32 s7, s5, 0
	s_add_u32 s6, s6, s0
	s_addc_u32 s7, s7, 0
	s_mul_i32 s0, s43, 0x1800000
	s_add_u32 s96, s6, s0
	s_addc_u32 s97, s7, 0
	s_mul_i32 s0, s43, 0x300000
	s_add_u32 s6, s6, s0
	s_addc_u32 s7, s7, 0
	s_add_u32 s6, s6, 0xc000000
	s_addc_u32 s7, s7, 0
	s_lshl_b32 s0, s81, 6
	s_add_u32 s0, s0, 0x180
	s_mul_i32 s0, s0, 0x9000
	s_add_u32 s8, s4, 0x17700000
	s_addc_u32 s9, s5, 0
	s_add_u32 s8, s8, s0
	s_addc_u32 s9, s9, 0
	s_lshl_b32 s0, s43, 12
	s_add_u32 s98, s8, s0
	s_addc_u32 s99, s9, 0
	s_lshl_b32 s0, s43, 9
	s_add_u32 s0, s0, 0x8000
	s_add_u32 s8, s8, s0
	s_addc_u32 s9, s9, 0
	s_lshl_b32 s0, s43, 11
	s_lshl_b32 s92, s80, 7
	s_add_u32 s0, s0, s92
	s_lshl_b32 s92, s21, 4
	s_add_u32 s0, s0, s92
	v_and_b32_e32 v146, 15, v144
	v_add_u32_e32 v146, s0, v146
	v_lshrrev_b32_e32 v147, 4, v144
	s_lshl_b32 s92, s81, 8
	s_add_u32 s92, s92, 0x700
	v_lshl_add_u32 v148, v147, 4, s92
	v_mov_b32_e32 v149, 0
	s_movk_i32 s93, 0x3000
	v_mad_u64_u32 v[82:83], s[90:91], v146, s93, v[148:149]
	s_add_u32 s90, s4, 0x9f00000
	s_addc_u32 s91, s5, 0
	v_lshl_add_u64 v[82:83], v[82:83], 0, s[90:91]
	global_load_dwordx4 v[2:5], v[82:83], off
	global_load_dwordx4 v[6:9], v[82:83], off offset:64
	global_load_dwordx4 v[10:13], v[82:83], off offset:128
	global_load_dwordx4 v[14:17], v[82:83], off offset:192
	s_lshl_b32 s92, s81, 8
	s_add_u32 s92, s92, 0x400
	v_lshl_add_u32 v148, v147, 3, s92
	v_lshlrev_b32_e32 v150, 11, v146
	v_add_u32_e32 v148, v148, v150
	s_add_u32 s90, s4, 0x1e300000
	s_addc_u32 s91, s5, 0
	v_lshl_add_u64 v[84:85], s[90:91], 0, v[148:149]
	v_mov_b32_e32 v100, 0
	v_mov_b32_e32 v101, 0
	v_mov_b32_e32 v102, 0
	v_mov_b32_e32 v103, 0
	v_mov_b32_e32 v104, 0
	v_mov_b32_e32 v105, 0
	v_mov_b32_e32 v106, 0
	v_mov_b32_e32 v107, 0
	v_mov_b32_e32 v108, 0
	v_mov_b32_e32 v109, 0
	v_mov_b32_e32 v110, 0
	v_mov_b32_e32 v111, 0
	v_mov_b32_e32 v112, 0
	v_mov_b32_e32 v113, 0
	v_mov_b32_e32 v114, 0
	v_mov_b32_e32 v115, 0
	v_mov_b32_e32 v116, 0
	v_mov_b32_e32 v117, 0
	v_mov_b32_e32 v118, 0
	v_mov_b32_e32 v119, 0
	v_mov_b32_e32 v120, 0
	v_mov_b32_e32 v121, 0
	v_mov_b32_e32 v122, 0
	v_mov_b32_e32 v123, 0
	v_mov_b32_e32 v124, 0
	v_mov_b32_e32 v125, 0
	v_mov_b32_e32 v126, 0
	v_mov_b32_e32 v127, 0
	v_mov_b32_e32 v128, 0
	v_mov_b32_e32 v129, 0
	v_mov_b32_e32 v130, 0
	v_mov_b32_e32 v131, 0
	v_mov_b32_e32 v132, 0xf149f2ca
	v_mov_b32_e32 v133, 0xf149f2ca
	v_mov_b32_e32 v134, 0
	v_mov_b32_e32 v135, 0
	s_mov_b32 s89, 0
	s_mov_b32 s42, 36
	s_barrier
	s_cmp_eq_u32 s89, 4
	s_cbranch_scc0 .Lga_nosw1
	s_mov_b64 s[6:7], s[96:97]
	s_mov_b64 s[8:9], s[98:99]

.Lga_nosw3:
	s_add_i32 m0, s32, 32768
	s_nop 0
	global_load_lds_dwordx4 v142, s[6:7]
	s_add_i32 m0, s41, 32768
	s_nop 0
	global_load_lds_dwordx4 v143, s[8:9]
	s_add_u32 s6, s6, 0xc0000
	s_addc_u32 s7, s7, 0
	s_add_u32 s8, s8, 0x80
	s_addc_u32 s9, s9, 0
	s_add_u32 s89, s89, 1
	s_cmp_eq_u32 s89, 4
	s_cbranch_scc0 .Lga_nosw4
	s_mov_b64 s[6:7], s[96:97]
	s_mov_b64 s[8:9], s[98:99]
.Lga_nosw4:
	s_add_i32 m0, s32, 49152
	s_nop 0
	global_load_lds_dwordx4 v142, s[6:7]
	s_add_i32 m0, s41, 49152
	s_nop 0
	global_load_lds_dwordx4 v143, s[8:9]
	s_add_u32 s6, s6, 0xc0000
	s_addc_u32 s7, s7, 0
	s_add_u32 s8, s8, 0x80
	s_addc_u32 s9, s9, 0
	s_add_u32 s89, s89, 1
	s_waitcnt vmcnt(6)
	s_barrier
	s_bitcmp1_b32 s101, 0
	s_cbranch_scc1 .Lga_loop
	ds_read_b128 v[18:21], v136 offset:0
	ds_read_b128 v[22:25], v137 offset:0
	ds_read_b128 v[26:29], v136 offset:2048
	ds_read_b128 v[30:33], v137 offset:2048
	ds_read_b128 v[34:37], v136 offset:4096
	ds_read_b128 v[38:41], v137 offset:4096
	ds_read_b128 v[42:45], v136 offset:6144
	ds_read_b128 v[46:49], v137 offset:6144
.Lga_loop:
	s_bitcmp1_b32 s101, 0
	s_cbranch_scc1 .Lga_sync0
	s_waitcnt lgkmcnt(0)
	v_mfma_f32_16x16x32_bf16 v[50:53], v[18:21], v[2:5], 0
	v_mfma_f32_16x16x32_bf16 v[54:57], v[26:29], v[2:5], 0
	v_mfma_f32_16x16x32_bf16 v[58:61], v[34:37], v[2:5], 0
	v_mfma_f32_16x16x32_bf16 v[62:65], v[42:45], v[2:5], 0
	v_mfma_f32_16x16x32_bf16 v[50:53], v[22:25], v[6:9], v[50:53]
	v_mfma_f32_16x16x32_bf16 v[54:57], v[30:33], v[6:9], v[54:57]
	v_mfma_f32_16x16x32_bf16 v[58:61], v[38:41], v[6:9], v[58:61]
	v_mfma_f32_16x16x32_bf16 v[62:65], v[46:49], v[6:9], v[62:65]
	ds_read_b64 v[168:169], v138 offset:0
	ds_read_b64 v[170:171], v139 offset:0
	ds_read_b64 v[172:173], v140 offset:0
	ds_read_b64 v[174:175], v141 offset:0
	ds_read_b64 v[176:177], v138 offset:2048
	ds_read_b64 v[178:179], v139 offset:2048
	ds_read_b64 v[180:181], v140 offset:2048
	ds_read_b64 v[182:183], v141 offset:2048
	v_mfma_f32_16x16x32_bf16 v[66:69], v[18:21], v[10:13], 0
	v_mfma_f32_16x16x32_bf16 v[70:73], v[26:29], v[10:13], 0
	v_mfma_f32_16x16x32_bf16 v[74:77], v[34:37], v[10:13], 0
	v_mfma_f32_16x16x32_bf16 v[78:81], v[42:45], v[10:13], 0
	v_mfma_f32_16x16x32_bf16 v[66:69], v[22:25], v[14:17], v[66:69]
	v_mfma_f32_16x16x32_bf16 v[70:73], v[30:33], v[14:17], v[70:73]
	v_mfma_f32_16x16x32_bf16 v[74:77], v[38:41], v[14:17], v[74:77]
	v_mfma_f32_16x16x32_bf16 v[78:81], v[46:49], v[14:17], v[78:81]
	ds_read_b64 v[184:185], v138 offset:4096
	ds_read_b64 v[186:187], v139 offset:4096
	ds_read_b64 v[188:189], v140 offset:4096
	ds_read_b64 v[190:191], v141 offset:4096
	ds_read_b64 v[192:193], v138 offset:6144
	ds_read_b64 v[194:195], v139 offset:6144
	ds_read_b64 v[196:197], v140 offset:6144
	ds_read_b64 v[198:199], v141 offset:6144
	s_waitcnt lgkmcnt(0)
.Lga_sync0:
	s_cmp_eq_u32 s42, 1
	s_cbranch_scc1 .Lga_cmp0
	s_cmp_lt_u32 s42, 4
	s_cbranch_scc1 .Lga_tail0
	s_waitcnt vmcnt(4)
	s_branch .Lga_bar0

.Lga_bar0:
	s_barrier
	s_cmp_lt_u32 s42, 5
	s_cbranch_scc1 .Lga_go0
	s_cmp_eq_u32 s89, 4
	s_cbranch_scc0 .Lga_nosw5
	s_mov_b64 s[6:7], s[96:97]
	s_mov_b64 s[8:9], s[98:99]
.Lga_nosw5:
	s_add_i32 m0, s32, 0
	s_nop 0
	global_load_lds_dwordx4 v142, s[6:7]
	s_add_i32 m0, s41, 0
	s_nop 0
	global_load_lds_dwordx4 v143, s[8:9]
	s_add_u32 s6, s6, 0xc0000
	s_addc_u32 s7, s7, 0
	s_add_u32 s8, s8, 0x80
	s_addc_u32 s9, s9, 0
	s_add_u32 s89, s89, 1
.Lga_go0:
	s_bitcmp1_b32 s101, 0
	s_cbranch_scc1 .Lga_idle0
	ds_read_b128 v[18:21], v136 offset:16384
	ds_read_b128 v[22:25], v137 offset:16384
	ds_read_b128 v[26:29], v136 offset:18432
	ds_read_b128 v[30:33], v137 offset:18432
	ds_read_b128 v[34:37], v136 offset:20480
	ds_read_b128 v[38:41], v137 offset:20480
	ds_read_b128 v[42:45], v136 offset:22528
	ds_read_b128 v[46:49], v137 offset:22528
.Lga_cmp0:
	s_bitcmp1_b32 s101, 0
	s_cbranch_scc1 .Lga_idle0
	s_nop 3
	v_max3_f32 v144, v50, v51, v52
	v_max3_f32 v145, v53, v54, v55
	v_max3_f32 v150, v56, v57, v58
	v_max3_f32 v151, v59, v60, v61
	v_max3_f32 v152, v62, v63, v64
	v_max3_f32 v144, v144, v145, v65
	v_max3_f32 v144, v144, v150, v151
	v_max_f32_e32 v144, v144, v152
	v_mov_b32_e32 v145, v144
	s_nop 1
	v_permlane16_swap_b32_e32 v144, v145
	v_max_f32_e32 v144, v144, v145
	v_mov_b32_e32 v145, v144
	s_nop 1
	v_permlane32_swap_b32_e32 v144, v145
	v_max_f32_e32 v144, v144, v145
	v_mul_f32_e32 v144, s100, v144
	v_max_f32_e32 v146, v132, v144
	v_cmp_gt_f32_e32 vcc, v146, v132
	s_cbranch_vccz .Lga_nors1
	v_sub_f32_e32 v148, v132, v146
	v_exp_f32_e32 v148, v148
	v_mov_b32_e32 v132, v146
	s_nop 0
	v_mul_f32_e32 v134, v134, v148
	v_pk_mul_f32 v[100:101], v[100:101], v[148:149] op_sel_hi:[1,0]
	v_pk_mul_f32 v[102:103], v[102:103], v[148:149] op_sel_hi:[1,0]
	v_pk_mul_f32 v[104:105], v[104:105], v[148:149] op_sel_hi:[1,0]
	v_pk_mul_f32 v[106:107], v[106:107], v[148:149] op_sel_hi:[1,0]
	v_pk_mul_f32 v[108:109], v[108:109], v[148:149] op_sel_hi:[1,0]
	v_pk_mul_f32 v[110:111], v[110:111], v[148:149] op_sel_hi:[1,0]
	v_pk_mul_f32 v[112:113], v[112:113], v[148:149] op_sel_hi:[1,0]
	v_pk_mul_f32 v[114:115], v[114:115], v[148:149] op_sel_hi:[1,0]
.Lga_nors1:
	v_pk_fma_f32 v[50:51], v[50:51], v[86:87], v[146:147] op_sel_hi:[1,0,0] neg_lo:[0,0,1] neg_hi:[0,0,1]
	v_pk_fma_f32 v[52:53], v[52:53], v[86:87], v[146:147] op_sel_hi:[1,0,0] neg_lo:[0,0,1] neg_hi:[0,0,1]
	v_pk_fma_f32 v[54:55], v[54:55], v[86:87], v[146:147] op_sel_hi:[1,0,0] neg_lo:[0,0,1] neg_hi:[0,0,1]
	v_pk_fma_f32 v[56:57], v[56:57], v[86:87], v[146:147] op_sel_hi:[1,0,0] neg_lo:[0,0,1] neg_hi:[0,0,1]
	v_pk_fma_f32 v[58:59], v[58:59], v[86:87], v[146:147] op_sel_hi:[1,0,0] neg_lo:[0,0,1] neg_hi:[0,0,1]
	v_pk_fma_f32 v[60:61], v[60:61], v[86:87], v[146:147] op_sel_hi:[1,0,0] neg_lo:[0,0,1] neg_hi:[0,0,1]
	v_pk_fma_f32 v[62:63], v[62:63], v[86:87], v[146:147] op_sel_hi:[1,0,0] neg_lo:[0,0,1] neg_hi:[0,0,1]
	v_pk_fma_f32 v[64:65], v[64:65], v[86:87], v[146:147] op_sel_hi:[1,0,0] neg_lo:[0,0,1] neg_hi:[0,0,1]
	v_exp_f32_e32 v50, v50
	v_exp_f32_e32 v51, v51
	v_exp_f32_e32 v52, v52
	v_exp_f32_e32 v53, v53
	v_exp_f32_e32 v54, v54
	v_exp_f32_e32 v55, v55
	v_exp_f32_e32 v56, v56
	v_exp_f32_e32 v57, v57
	v_exp_f32_e32 v58, v58
	v_exp_f32_e32 v59, v59
	v_exp_f32_e32 v60, v60
	v_exp_f32_e32 v61, v61
	v_exp_f32_e32 v62, v62
	v_exp_f32_e32 v63, v63
	v_exp_f32_e32 v64, v64
	v_exp_f32_e32 v65, v65
	v_pk_add_f32 v[150:151], v[50:51], v[52:53]
	v_pk_add_f32 v[152:153], v[54:55], v[56:57]
	v_pk_add_f32 v[154:155], v[58:59], v[60:61]
	v_pk_add_f32 v[156:157], v[62:63], v[64:65]
	v_pk_add_f32 v[150:151], v[150:151], v[152:153]
	v_pk_add_f32 v[154:155], v[154:155], v[156:157]
	v_pk_add_f32 v[150:151], v[150:151], v[154:155]
	v_add_f32_e32 v150, v150, v151
	v_add_f32_e32 v134, v134, v150
	v_cvt_pk_bf16_f32 v200, v50, v51
	v_cvt_pk_bf16_f32 v201, v52, v53
	v_cvt_pk_bf16_f32 v202, v54, v55
	v_cvt_pk_bf16_f32 v203, v56, v57
	v_cvt_pk_bf16_f32 v204, v58, v59
	v_cvt_pk_bf16_f32 v205, v60, v61
	v_cvt_pk_bf16_f32 v206, v62, v63
	v_cvt_pk_bf16_f32 v207, v64, v65
	s_nop 1
	v_mfma_f32_16x16x32_bf16 v[100:103], v[168:171], v[200:203], v[100:103]
	v_mfma_f32_16x16x32_bf16 v[100:103], v[172:175], v[204:207], v[100:103]
	v_mfma_f32_16x16x32_bf16 v[104:107], v[176:179], v[200:203], v[104:107]
	v_mfma_f32_16x16x32_bf16 v[104:107], v[180:183], v[204:207], v[104:107]
	v_mfma_f32_16x16x32_bf16 v[108:111], v[184:187], v[200:203], v[108:111]
	v_mfma_f32_16x16x32_bf16 v[108:111], v[188:191], v[204:207], v[108:111]
	v_mfma_f32_16x16x32_bf16 v[112:115], v[192:195], v[200:203], v[112:115]
	v_mfma_f32_16x16x32_bf16 v[112:115], v[196:199], v[204:207], v[112:115]
	v_max3_f32 v144, v66, v67, v68
	v_max3_f32 v145, v69, v70, v71
	v_max3_f32 v150, v72, v73, v74
	v_max3_f32 v151, v75, v76, v77
	v_max3_f32 v152, v78, v79, v80
	v_max3_f32 v144, v144, v145, v81
	v_max3_f32 v144, v144, v150, v151
	v_max_f32_e32 v144, v144, v152
	v_mov_b32_e32 v145, v144
	s_nop 1
	v_permlane16_swap_b32_e32 v144, v145
	v_max_f32_e32 v144, v144, v145
	v_mov_b32_e32 v145, v144
	s_nop 1
	v_permlane32_swap_b32_e32 v144, v145
	v_max_f32_e32 v144, v144, v145
	v_mul_f32_e32 v144, s100, v144
	v_max_f32_e32 v146, v133, v144
	v_cmp_gt_f32_e32 vcc, v146, v133
	s_cbranch_vccz .Lga_nors2
	v_sub_f32_e32 v148, v133, v146
	v_exp_f32_e32 v148, v148
	v_mov_b32_e32 v133, v146
	s_nop 0
	v_mul_f32_e32 v135, v135, v148
	v_pk_mul_f32 v[116:117], v[116:117], v[148:149] op_sel_hi:[1,0]
	v_pk_mul_f32 v[118:119], v[118:119], v[148:149] op_sel_hi:[1,0]
	v_pk_mul_f32 v[120:121], v[120:121], v[148:149] op_sel_hi:[1,0]
	v_pk_mul_f32 v[122:123], v[122:123], v[148:149] op_sel_hi:[1,0]
	v_pk_mul_f32 v[124:125], v[124:125], v[148:149] op_sel_hi:[1,0]
	v_pk_mul_f32 v[126:127], v[126:127], v[148:149] op_sel_hi:[1,0]
	v_pk_mul_f32 v[128:129], v[128:129], v[148:149] op_sel_hi:[1,0]
	v_pk_mul_f32 v[130:131], v[130:131], v[148:149] op_sel_hi:[1,0]

.Lga_idle0:
	s_sub_u32 s42, s42, 1
	s_bitcmp1_b32 s101, 0
	s_cbranch_scc1 .Lga_sync1
	s_waitcnt lgkmcnt(0)
	v_mfma_f32_16x16x32_bf16 v[50:53], v[18:21], v[2:5], 0
	v_mfma_f32_16x16x32_bf16 v[54:57], v[26:29], v[2:5], 0
	v_mfma_f32_16x16x32_bf16 v[58:61], v[34:37], v[2:5], 0
	v_mfma_f32_16x16x32_bf16 v[62:65], v[42:45], v[2:5], 0
	v_mfma_f32_16x16x32_bf16 v[50:53], v[22:25], v[6:9], v[50:53]
	v_mfma_f32_16x16x32_bf16 v[54:57], v[30:33], v[6:9], v[54:57]
	v_mfma_f32_16x16x32_bf16 v[58:61], v[38:41], v[6:9], v[58:61]
	v_mfma_f32_16x16x32_bf16 v[62:65], v[46:49], v[6:9], v[62:65]
	ds_read_b64 v[168:169], v138 offset:16384
	ds_read_b64 v[170:171], v139 offset:16384
	ds_read_b64 v[172:173], v140 offset:16384
	ds_read_b64 v[174:175], v141 offset:16384
	ds_read_b64 v[176:177], v138 offset:18432
	ds_read_b64 v[178:179], v139 offset:18432
	ds_read_b64 v[180:181], v140 offset:18432
	ds_read_b64 v[182:183], v141 offset:18432
	v_mfma_f32_16x16x32_bf16 v[66:69], v[18:21], v[10:13], 0
	v_mfma_f32_16x16x32_bf16 v[70:73], v[26:29], v[10:13], 0
	v_mfma_f32_16x16x32_bf16 v[74:77], v[34:37], v[10:13], 0
	v_mfma_f32_16x16x32_bf16 v[78:81], v[42:45], v[10:13], 0
	v_mfma_f32_16x16x32_bf16 v[66:69], v[22:25], v[14:17], v[66:69]
	v_mfma_f32_16x16x32_bf16 v[70:73], v[30:33], v[14:17], v[70:73]
	v_mfma_f32_16x16x32_bf16 v[74:77], v[38:41], v[14:17], v[74:77]
	v_mfma_f32_16x16x32_bf16 v[78:81], v[46:49], v[14:17], v[78:81]
	ds_read_b64 v[184:185], v138 offset:20480
	ds_read_b64 v[186:187], v139 offset:20480
	ds_read_b64 v[188:189], v140 offset:20480
	ds_read_b64 v[190:191], v141 offset:20480
	ds_read_b64 v[192:193], v138 offset:22528
	ds_read_b64 v[194:195], v139 offset:22528
	ds_read_b64 v[196:197], v140 offset:22528
	ds_read_b64 v[198:199], v141 offset:22528
	s_waitcnt lgkmcnt(0)

.Lga_nosw6:
	s_add_i32 m0, s32, 16384
	s_nop 0
	global_load_lds_dwordx4 v142, s[6:7]
	s_add_i32 m0, s41, 16384
	s_nop 0
	global_load_lds_dwordx4 v143, s[8:9]
	s_add_u32 s6, s6, 0xc0000
	s_addc_u32 s7, s7, 0
	s_add_u32 s8, s8, 0x80
	s_addc_u32 s9, s9, 0
	s_add_u32 s89, s89, 1
.Lga_go1:
	s_bitcmp1_b32 s101, 0
	s_cbranch_scc1 .Lga_idle1
	ds_read_b128 v[18:21], v136 offset:32768
	ds_read_b128 v[22:25], v137 offset:32768
	ds_read_b128 v[26:29], v136 offset:34816
	ds_read_b128 v[30:33], v137 offset:34816
	ds_read_b128 v[34:37], v136 offset:36864
	ds_read_b128 v[38:41], v137 offset:36864
	ds_read_b128 v[42:45], v136 offset:38912
	ds_read_b128 v[46:49], v137 offset:38912

.Lga_idle1:
	s_sub_u32 s42, s42, 1
	s_bitcmp1_b32 s101, 0
	s_cbranch_scc1 .Lga_sync2
	s_waitcnt lgkmcnt(0)
	v_mfma_f32_16x16x32_bf16 v[50:53], v[18:21], v[2:5], 0
	v_mfma_f32_16x16x32_bf16 v[54:57], v[26:29], v[2:5], 0
	v_mfma_f32_16x16x32_bf16 v[58:61], v[34:37], v[2:5], 0
	v_mfma_f32_16x16x32_bf16 v[62:65], v[42:45], v[2:5], 0
	v_mfma_f32_16x16x32_bf16 v[50:53], v[22:25], v[6:9], v[50:53]
	v_mfma_f32_16x16x32_bf16 v[54:57], v[30:33], v[6:9], v[54:57]
	v_mfma_f32_16x16x32_bf16 v[58:61], v[38:41], v[6:9], v[58:61]
	v_mfma_f32_16x16x32_bf16 v[62:65], v[46:49], v[6:9], v[62:65]
	ds_read_b64 v[168:169], v138 offset:32768
	ds_read_b64 v[170:171], v139 offset:32768
	ds_read_b64 v[172:173], v140 offset:32768
	ds_read_b64 v[174:175], v141 offset:32768
	ds_read_b64 v[176:177], v138 offset:34816
	ds_read_b64 v[178:179], v139 offset:34816
	ds_read_b64 v[180:181], v140 offset:34816
	ds_read_b64 v[182:183], v141 offset:34816
	v_mfma_f32_16x16x32_bf16 v[66:69], v[18:21], v[10:13], 0
	v_mfma_f32_16x16x32_bf16 v[70:73], v[26:29], v[10:13], 0
	v_mfma_f32_16x16x32_bf16 v[74:77], v[34:37], v[10:13], 0
	v_mfma_f32_16x16x32_bf16 v[78:81], v[42:45], v[10:13], 0
	v_mfma_f32_16x16x32_bf16 v[66:69], v[22:25], v[14:17], v[66:69]
	v_mfma_f32_16x16x32_bf16 v[70:73], v[30:33], v[14:17], v[70:73]
	v_mfma_f32_16x16x32_bf16 v[74:77], v[38:41], v[14:17], v[74:77]
	v_mfma_f32_16x16x32_bf16 v[78:81], v[46:49], v[14:17], v[78:81]
	ds_read_b64 v[184:185], v138 offset:36864
	ds_read_b64 v[186:187], v139 offset:36864
	ds_read_b64 v[188:189], v140 offset:36864
	ds_read_b64 v[190:191], v141 offset:36864
	ds_read_b64 v[192:193], v138 offset:38912
	ds_read_b64 v[194:195], v139 offset:38912
	ds_read_b64 v[196:197], v140 offset:38912
	ds_read_b64 v[198:199], v141 offset:38912
	s_waitcnt lgkmcnt(0)

.Lga_nosw7:
	s_add_i32 m0, s32, 32768
	s_nop 0
	global_load_lds_dwordx4 v142, s[6:7]
	s_add_i32 m0, s41, 32768
	s_nop 0
	global_load_lds_dwordx4 v143, s[8:9]
	s_add_u32 s6, s6, 0xc0000
	s_addc_u32 s7, s7, 0
	s_add_u32 s8, s8, 0x80
	s_addc_u32 s9, s9, 0
	s_add_u32 s89, s89, 1
.Lga_go2:
	s_bitcmp1_b32 s101, 0
	s_cbranch_scc1 .Lga_idle2
	ds_read_b128 v[18:21], v136 offset:49152
	ds_read_b128 v[22:25], v137 offset:49152
	ds_read_b128 v[26:29], v136 offset:51200
	ds_read_b128 v[30:33], v137 offset:51200
	ds_read_b128 v[34:37], v136 offset:53248
	ds_read_b128 v[38:41], v137 offset:53248
	ds_read_b128 v[42:45], v136 offset:55296
	ds_read_b128 v[46:49], v137 offset:55296

.Lga_idle2:
	s_sub_u32 s42, s42, 1
	s_bitcmp1_b32 s101, 0
	s_cbranch_scc1 .Lga_sync3
	s_waitcnt lgkmcnt(0)
	v_mfma_f32_16x16x32_bf16 v[50:53], v[18:21], v[2:5], 0
	v_mfma_f32_16x16x32_bf16 v[54:57], v[26:29], v[2:5], 0
	v_mfma_f32_16x16x32_bf16 v[58:61], v[34:37], v[2:5], 0
	v_mfma_f32_16x16x32_bf16 v[62:65], v[42:45], v[2:5], 0
	v_mfma_f32_16x16x32_bf16 v[50:53], v[22:25], v[6:9], v[50:53]
	v_mfma_f32_16x16x32_bf16 v[54:57], v[30:33], v[6:9], v[54:57]
	v_mfma_f32_16x16x32_bf16 v[58:61], v[38:41], v[6:9], v[58:61]
	v_mfma_f32_16x16x32_bf16 v[62:65], v[46:49], v[6:9], v[62:65]
	ds_read_b64 v[168:169], v138 offset:49152
	ds_read_b64 v[170:171], v139 offset:49152
	ds_read_b64 v[172:173], v140 offset:49152
	ds_read_b64 v[174:175], v141 offset:49152
	ds_read_b64 v[176:177], v138 offset:51200
	ds_read_b64 v[178:179], v139 offset:51200
	ds_read_b64 v[180:181], v140 offset:51200
	ds_read_b64 v[182:183], v141 offset:51200
	v_mfma_f32_16x16x32_bf16 v[66:69], v[18:21], v[10:13], 0
	v_mfma_f32_16x16x32_bf16 v[70:73], v[26:29], v[10:13], 0
	v_mfma_f32_16x16x32_bf16 v[74:77], v[34:37], v[10:13], 0
	v_mfma_f32_16x16x32_bf16 v[78:81], v[42:45], v[10:13], 0
	v_mfma_f32_16x16x32_bf16 v[66:69], v[22:25], v[14:17], v[66:69]
	v_mfma_f32_16x16x32_bf16 v[70:73], v[30:33], v[14:17], v[70:73]
	v_mfma_f32_16x16x32_bf16 v[74:77], v[38:41], v[14:17], v[74:77]
	v_mfma_f32_16x16x32_bf16 v[78:81], v[46:49], v[14:17], v[78:81]
	ds_read_b64 v[184:185], v138 offset:53248
	ds_read_b64 v[186:187], v139 offset:53248
	ds_read_b64 v[188:189], v140 offset:53248
	ds_read_b64 v[190:191], v141 offset:53248
	ds_read_b64 v[192:193], v138 offset:55296
	ds_read_b64 v[194:195], v139 offset:55296
	ds_read_b64 v[196:197], v140 offset:55296
	ds_read_b64 v[198:199], v141 offset:55296
	s_waitcnt lgkmcnt(0)

.Lga_nosw8:
	s_add_i32 m0, s32, 49152
	s_nop 0
	global_load_lds_dwordx4 v142, s[6:7]
	s_add_i32 m0, s41, 49152
	s_nop 0
	global_load_lds_dwordx4 v143, s[8:9]
	s_add_u32 s6, s6, 0xc0000
	s_addc_u32 s7, s7, 0
	s_add_u32 s8, s8, 0x80
	s_addc_u32 s9, s9, 0
	s_add_u32 s89, s89, 1
.Lga_go3:
	s_bitcmp1_b32 s101, 0
	s_cbranch_scc1 .Lga_idle3
	ds_read_b128 v[18:21], v136 offset:0
	ds_read_b128 v[22:25], v137 offset:0
	ds_read_b128 v[26:29], v136 offset:2048
	ds_read_b128 v[30:33], v137 offset:2048
	ds_read_b128 v[34:37], v136 offset:4096
	ds_read_b128 v[38:41], v137 offset:4096
	ds_read_b128 v[42:45], v136 offset:6144
	ds_read_b128 v[46:49], v137 offset:6144
